# peerq top-16: sorting-network scan (4x sort16 + bitonic merges) and bitonic merge of half-row lists, bit-identical results
# speedup vs baseline: 1.0202x; 1.0087x over previous
.LBB0_42:
	v_add_u32_e32 v0, 0x400, v154
	ds_write2_b32 v154, v50, v34 offset1:32
	ds_write2_b32 v154, v51, v35 offset0:129 offset1:161
	ds_write2_b32 v0, v52, v36 offset0:2 offset1:34
	ds_write2_b32 v0, v53, v37 offset0:131 offset1:163
	v_add_u32_e32 v0, 0x1000, v154
	ds_write2_b32 v0, v54, v38 offset0:8 offset1:40
	ds_write2_b32 v0, v55, v39 offset0:137 offset1:169
	v_add_u32_e32 v0, 0x1400, v154
	ds_write2_b32 v0, v56, v40 offset0:10 offset1:42
	ds_write2_b32 v0, v57, v41 offset0:139 offset1:171
	v_add_u32_e32 v0, 0x2000, v154
	ds_write2_b32 v0, v58, v42 offset0:16 offset1:48
	ds_write2_b32 v0, v59, v43 offset0:145 offset1:177
	v_add_u32_e32 v0, 0x2400, v154
	ds_write2_b32 v0, v60, v44 offset0:18 offset1:50
	ds_write2_b32 v0, v61, v45 offset0:147 offset1:179
	v_add_u32_e32 v0, 0x3000, v154
	ds_write2_b32 v0, v62, v46 offset0:24 offset1:56
	ds_write2_b32 v0, v63, v47 offset0:153 offset1:185
	v_add_u32_e32 v0, 0x3400, v154
	ds_write2_b32 v0, v64, v48 offset0:26 offset1:58
	ds_write2_b32 v0, v65, v49 offset0:155 offset1:187
	v_add_u32_e32 v0, 0x4000, v154
	ds_write2_b32 v0, v18, v2 offset0:32 offset1:64
	ds_write2_b32 v0, v19, v3 offset0:161 offset1:193
	v_add_u32_e32 v0, 0x4400, v154
	ds_write2_b32 v0, v20, v4 offset0:34 offset1:66
	ds_write2_b32 v0, v21, v5 offset0:163 offset1:195
	v_add_u32_e32 v0, 0x5000, v154
	ds_write2_b32 v0, v22, v6 offset0:40 offset1:72
	ds_write2_b32 v0, v23, v7 offset0:169 offset1:201
	v_add_u32_e32 v0, 0x5400, v154
	ds_write2_b32 v0, v24, v8 offset0:42 offset1:74
	ds_write2_b32 v0, v25, v9 offset0:171 offset1:203
	v_add_u32_e32 v0, 0x6000, v154
	ds_write2_b32 v0, v26, v10 offset0:48 offset1:80
	ds_write2_b32 v0, v27, v11 offset0:177 offset1:209
	v_add_u32_e32 v0, 0x6400, v154
	ds_write2_b32 v0, v28, v12 offset0:50 offset1:82
	ds_write2_b32 v0, v29, v13 offset0:179 offset1:211
	v_add_u32_e32 v0, 0x7000, v154
	ds_write2_b32 v0, v30, v14 offset0:56 offset1:88
	ds_write2_b32 v0, v31, v15 offset0:185 offset1:217
	v_add_u32_e32 v0, 0x7400, v154
	ds_write2_b32 v0, v32, v16 offset0:58 offset1:90
	ds_write2_b32 v0, v33, v17 offset0:187 offset1:219
	v_mov_b32_e32 v2, 0xff800000
	s_mov_b32 s4, 0
	v_mov_b32_e32 v0, v156
	v_mov_b32_e32 v3, 0xff800000
	v_mov_b32_e32 v4, 0xff800000
	v_mov_b32_e32 v5, 0xff800000
	v_mov_b32_e32 v6, 0xff800000
	v_mov_b32_e32 v7, 0xff800000
	v_mov_b32_e32 v8, 0xff800000
	v_mov_b32_e32 v9, 0xff800000
	v_mov_b32_e32 v10, 0xff800000
	v_mov_b32_e32 v11, 0xff800000
	v_mov_b32_e32 v12, 0xff800000
	v_mov_b32_e32 v13, 0xff800000
	v_mov_b32_e32 v14, 0xff800000
	v_mov_b32_e32 v15, 0xff800000
	v_mov_b32_e32 v16, 0xff800000
	v_mov_b32_e32 v17, 0xff800000
	s_waitcnt lgkmcnt(0)
	s_barrier
	ds_read2_b32 v[98:99], v156 offset1:1
	ds_read2_b32 v[100:101], v156 offset0:2 offset1:3
	ds_read2_b32 v[102:103], v156 offset0:4 offset1:5
	ds_read2_b32 v[104:105], v156 offset0:6 offset1:7
	ds_read2_b32 v[106:107], v156 offset0:8 offset1:9
	ds_read2_b32 v[108:109], v156 offset0:10 offset1:11
	ds_read2_b32 v[110:111], v156 offset0:12 offset1:13
	ds_read2_b32 v[112:113], v156 offset0:14 offset1:15
	ds_read2_b32 v[114:115], v156 offset0:16 offset1:17
	ds_read2_b32 v[116:117], v156 offset0:18 offset1:19
	ds_read2_b32 v[118:119], v156 offset0:20 offset1:21
	ds_read2_b32 v[120:121], v156 offset0:22 offset1:23
	ds_read2_b32 v[122:123], v156 offset0:24 offset1:25
	ds_read2_b32 v[124:125], v156 offset0:26 offset1:27
	ds_read2_b32 v[126:127], v156 offset0:28 offset1:29
	ds_read2_b32 v[128:129], v156 offset0:30 offset1:31
	ds_read2_b32 v[162:163], v156 offset0:32 offset1:33
	ds_read2_b32 v[164:165], v156 offset0:34 offset1:35
	ds_read2_b32 v[166:167], v156 offset0:36 offset1:37
	ds_read2_b32 v[168:169], v156 offset0:38 offset1:39
	ds_read2_b32 v[170:171], v156 offset0:40 offset1:41
	ds_read2_b32 v[172:173], v156 offset0:42 offset1:43
	ds_read2_b32 v[174:175], v156 offset0:44 offset1:45
	ds_read2_b32 v[176:177], v156 offset0:46 offset1:47
	ds_read2_b32 v[178:179], v156 offset0:48 offset1:49
	ds_read2_b32 v[180:181], v156 offset0:50 offset1:51
	ds_read2_b32 v[182:183], v156 offset0:52 offset1:53
	ds_read2_b32 v[184:185], v156 offset0:54 offset1:55
	ds_read2_b32 v[186:187], v156 offset0:56 offset1:57
	ds_read2_b32 v[188:189], v156 offset0:58 offset1:59
	ds_read2_b32 v[190:191], v156 offset0:60 offset1:61
	ds_read2_b32 v[192:193], v156 offset0:62 offset1:63
	s_waitcnt lgkmcnt(15)
	v_and_b32_e32 v98, 0xffffff80, v98
	v_or3_b32 v98, v155, v98, 0
	v_and_b32_e32 v99, 0xffffff80, v99
	v_or3_b32 v99, v155, v99, 1
	v_and_b32_e32 v100, 0xffffff80, v100
	v_or3_b32 v100, v155, v100, 2
	v_and_b32_e32 v101, 0xffffff80, v101
	v_or3_b32 v101, v155, v101, 3
	v_and_b32_e32 v102, 0xffffff80, v102
	v_or3_b32 v102, v155, v102, 4
	v_and_b32_e32 v103, 0xffffff80, v103
	v_or3_b32 v103, v155, v103, 5
	v_and_b32_e32 v104, 0xffffff80, v104
	v_or3_b32 v104, v155, v104, 6
	v_and_b32_e32 v105, 0xffffff80, v105
	v_or3_b32 v105, v155, v105, 7
	v_and_b32_e32 v106, 0xffffff80, v106
	v_or3_b32 v106, v155, v106, 8
	v_and_b32_e32 v107, 0xffffff80, v107
	v_or3_b32 v107, v155, v107, 9
	v_and_b32_e32 v108, 0xffffff80, v108
	v_or3_b32 v108, v155, v108, 10
	v_and_b32_e32 v109, 0xffffff80, v109
	v_or3_b32 v109, v155, v109, 11
	v_and_b32_e32 v110, 0xffffff80, v110
	v_or3_b32 v110, v155, v110, 12
	v_and_b32_e32 v111, 0xffffff80, v111
	v_or3_b32 v111, v155, v111, 13
	v_and_b32_e32 v112, 0xffffff80, v112
	v_or3_b32 v112, v155, v112, 14
	v_and_b32_e32 v113, 0xffffff80, v113
	v_or3_b32 v113, v155, v113, 15
	v_max_f32_e32 v18, v98, v99
	v_min_f32_e32 v19, v98, v99
	v_max_f32_e32 v98, v100, v101
	v_min_f32_e32 v99, v100, v101
	v_max_f32_e32 v100, v18, v98
	v_min_f32_e32 v101, v18, v98
	v_max_f32_e32 v18, v19, v99
	v_min_f32_e32 v98, v19, v99
	v_max_f32_e32 v19, v18, v101
	v_min_f32_e32 v99, v18, v101
	v_max_f32_e32 v18, v102, v103
	v_min_f32_e32 v101, v102, v103
	v_max_f32_e32 v102, v104, v105
	v_min_f32_e32 v103, v104, v105
	v_max_f32_e32 v104, v18, v102
	v_min_f32_e32 v105, v18, v102
	v_max_f32_e32 v18, v101, v103
	v_min_f32_e32 v102, v101, v103
	v_max_f32_e32 v101, v18, v105
	v_min_f32_e32 v103, v18, v105
	v_max_f32_e32 v18, v100, v104
	v_min_f32_e32 v105, v100, v104
	v_max_f32_e32 v100, v99, v103
	v_min_f32_e32 v104, v99, v103
	v_max_f32_e32 v99, v100, v105
	v_min_f32_e32 v103, v100, v105
	v_max_f32_e32 v100, v19, v101
	v_min_f32_e32 v105, v19, v101
	v_max_f32_e32 v19, v98, v102
	v_min_f32_e32 v101, v98, v102
	v_max_f32_e32 v98, v19, v105
	v_min_f32_e32 v102, v19, v105
	v_max_f32_e32 v19, v100, v99
	v_min_f32_e32 v105, v100, v99
	v_max_f32_e32 v100, v98, v103
	v_min_f32_e32 v99, v98, v103
	v_max_f32_e32 v98, v102, v104
	v_min_f32_e32 v103, v102, v104
	v_max_f32_e32 v102, v106, v107
	v_min_f32_e32 v104, v106, v107
	v_max_f32_e32 v106, v108, v109
	v_min_f32_e32 v107, v108, v109
	v_max_f32_e32 v108, v102, v106
	v_min_f32_e32 v109, v102, v106
	v_max_f32_e32 v102, v104, v107
	v_min_f32_e32 v106, v104, v107
	v_max_f32_e32 v104, v102, v109
	v_min_f32_e32 v107, v102, v109
	v_max_f32_e32 v102, v110, v111
	v_min_f32_e32 v109, v110, v111
	v_max_f32_e32 v110, v112, v113
	v_min_f32_e32 v111, v112, v113
	v_max_f32_e32 v112, v102, v110
	v_min_f32_e32 v113, v102, v110
	v_max_f32_e32 v102, v109, v111
	v_min_f32_e32 v110, v109, v111
	v_max_f32_e32 v109, v102, v113
	v_min_f32_e32 v111, v102, v113
	v_max_f32_e32 v102, v108, v112
	v_min_f32_e32 v113, v108, v112
	v_max_f32_e32 v108, v107, v111
	v_min_f32_e32 v112, v107, v111
	v_max_f32_e32 v107, v108, v113
	v_min_f32_e32 v111, v108, v113
	v_max_f32_e32 v108, v104, v109
	v_min_f32_e32 v113, v104, v109
	v_max_f32_e32 v104, v106, v110
	v_min_f32_e32 v109, v106, v110
	v_max_f32_e32 v106, v104, v113
	v_min_f32_e32 v110, v104, v113
	v_max_f32_e32 v104, v108, v107
	v_min_f32_e32 v113, v108, v107
	v_max_f32_e32 v108, v106, v111
	v_min_f32_e32 v107, v106, v111
	v_max_f32_e32 v106, v110, v112
	v_min_f32_e32 v111, v110, v112
	v_max_f32_e32 v110, v18, v102
	v_min_f32_e32 v112, v18, v102
	v_max_f32_e32 v18, v99, v107
	v_min_f32_e32 v102, v99, v107
	v_max_f32_e32 v99, v18, v112
	v_min_f32_e32 v107, v18, v112
	v_max_f32_e32 v18, v105, v113
	v_min_f32_e32 v112, v105, v113
	v_max_f32_e32 v105, v103, v111
	v_min_f32_e32 v113, v103, v111
	v_max_f32_e32 v103, v105, v112
	v_min_f32_e32 v111, v105, v112
	v_max_f32_e32 v105, v18, v99
	v_min_f32_e32 v112, v18, v99
	v_max_f32_e32 v18, v103, v107
	v_min_f32_e32 v99, v103, v107
	v_max_f32_e32 v103, v111, v102
	v_min_f32_e32 v107, v111, v102
	v_max_f32_e32 v111, v19, v104
	v_min_f32_e32 v102, v19, v104
	v_max_f32_e32 v19, v98, v106
	v_min_f32_e32 v104, v98, v106
	v_max_f32_e32 v98, v19, v102
	v_min_f32_e32 v106, v19, v102
	v_max_f32_e32 v19, v100, v108
	v_min_f32_e32 v102, v100, v108
	v_max_f32_e32 v100, v101, v109
	v_min_f32_e32 v108, v101, v109
	v_max_f32_e32 v101, v100, v102
	v_min_f32_e32 v109, v100, v102
	v_max_f32_e32 v100, v19, v98
	v_min_f32_e32 v102, v19, v98
	v_max_f32_e32 v19, v101, v106
	v_min_f32_e32 v98, v101, v106
	v_max_f32_e32 v101, v109, v104
	v_min_f32_e32 v106, v109, v104
	v_max_f32_e32 v109, v111, v105
	v_min_f32_e32 v104, v111, v105
	v_max_f32_e32 v111, v100, v112
	v_min_f32_e32 v105, v100, v112
	v_max_f32_e32 v100, v102, v18
	v_min_f32_e32 v112, v102, v18
	v_max_f32_e32 v102, v19, v99
	v_min_f32_e32 v18, v19, v99
	v_max_f32_e32 v19, v98, v103
	v_min_f32_e32 v99, v98, v103
	v_max_f32_e32 v98, v101, v107
	v_min_f32_e32 v103, v101, v107
	v_max_f32_e32 v101, v106, v113
	v_min_f32_e32 v107, v106, v113
	v_and_b32_e32 v114, 0xffffff80, v114
	v_or3_b32 v114, v155, v114, 16
	v_and_b32_e32 v115, 0xffffff80, v115
	v_or3_b32 v115, v155, v115, 17
	v_and_b32_e32 v116, 0xffffff80, v116
	v_or3_b32 v116, v155, v116, 18
	v_and_b32_e32 v117, 0xffffff80, v117
	v_or3_b32 v117, v155, v117, 19
	v_and_b32_e32 v118, 0xffffff80, v118
	v_or3_b32 v118, v155, v118, 20
	v_and_b32_e32 v119, 0xffffff80, v119
	v_or3_b32 v119, v155, v119, 21
	v_and_b32_e32 v120, 0xffffff80, v120
	v_or3_b32 v120, v155, v120, 22
	v_and_b32_e32 v121, 0xffffff80, v121
	v_or3_b32 v121, v155, v121, 23
	v_and_b32_e32 v122, 0xffffff80, v122
	v_or3_b32 v122, v155, v122, 24
	v_and_b32_e32 v123, 0xffffff80, v123
	v_or3_b32 v123, v155, v123, 25
	v_and_b32_e32 v124, 0xffffff80, v124
	v_or3_b32 v124, v155, v124, 26
	v_and_b32_e32 v125, 0xffffff80, v125
	v_or3_b32 v125, v155, v125, 27
	v_and_b32_e32 v126, 0xffffff80, v126
	v_or3_b32 v126, v155, v126, 28
	v_and_b32_e32 v127, 0xffffff80, v127
	v_or3_b32 v127, v155, v127, 29
	v_and_b32_e32 v128, 0xffffff80, v128
	v_or3_b32 v128, v155, v128, 30
	v_and_b32_e32 v129, 0xffffff80, v129
	v_or3_b32 v129, v155, v129, 31
	v_max_f32_e32 v106, v114, v115
	v_min_f32_e32 v113, v114, v115
	v_max_f32_e32 v114, v116, v117
	v_min_f32_e32 v115, v116, v117
	v_max_f32_e32 v116, v106, v114
	v_min_f32_e32 v117, v106, v114
	v_max_f32_e32 v106, v113, v115
	v_min_f32_e32 v114, v113, v115
	v_max_f32_e32 v113, v106, v117
	v_min_f32_e32 v115, v106, v117
	v_max_f32_e32 v106, v118, v119
	v_min_f32_e32 v117, v118, v119
	v_max_f32_e32 v118, v120, v121
	v_min_f32_e32 v119, v120, v121
	v_max_f32_e32 v120, v106, v118
	v_min_f32_e32 v121, v106, v118
	v_max_f32_e32 v106, v117, v119
	v_min_f32_e32 v118, v117, v119
	v_max_f32_e32 v117, v106, v121
	v_min_f32_e32 v119, v106, v121
	v_max_f32_e32 v106, v116, v120
	v_min_f32_e32 v121, v116, v120
	v_max_f32_e32 v116, v115, v119
	v_min_f32_e32 v120, v115, v119
	v_max_f32_e32 v115, v116, v121
	v_min_f32_e32 v119, v116, v121
	v_max_f32_e32 v116, v113, v117
	v_min_f32_e32 v121, v113, v117
	v_max_f32_e32 v113, v114, v118
	v_min_f32_e32 v117, v114, v118
	v_max_f32_e32 v114, v113, v121
	v_min_f32_e32 v118, v113, v121
	v_max_f32_e32 v113, v116, v115
	v_min_f32_e32 v121, v116, v115
	v_max_f32_e32 v116, v114, v119
	v_min_f32_e32 v115, v114, v119
	v_max_f32_e32 v114, v118, v120
	v_min_f32_e32 v119, v118, v120
	v_max_f32_e32 v118, v122, v123
	v_min_f32_e32 v120, v122, v123
	v_max_f32_e32 v122, v124, v125
	v_min_f32_e32 v123, v124, v125
	v_max_f32_e32 v124, v118, v122
	v_min_f32_e32 v125, v118, v122
	v_max_f32_e32 v118, v120, v123
	v_min_f32_e32 v122, v120, v123
	v_max_f32_e32 v120, v118, v125
	v_min_f32_e32 v123, v118, v125
	v_max_f32_e32 v118, v126, v127
	v_min_f32_e32 v125, v126, v127
	v_max_f32_e32 v126, v128, v129
	v_min_f32_e32 v127, v128, v129
	v_max_f32_e32 v128, v118, v126
	v_min_f32_e32 v129, v118, v126
	v_max_f32_e32 v118, v125, v127
	v_min_f32_e32 v126, v125, v127
	v_max_f32_e32 v125, v118, v129
	v_min_f32_e32 v127, v118, v129
	v_max_f32_e32 v118, v124, v128
	v_min_f32_e32 v129, v124, v128
	v_max_f32_e32 v124, v123, v127
	v_min_f32_e32 v128, v123, v127
	v_max_f32_e32 v123, v124, v129
	v_min_f32_e32 v127, v124, v129
	v_max_f32_e32 v124, v120, v125
	v_min_f32_e32 v129, v120, v125
	v_max_f32_e32 v120, v122, v126
	v_min_f32_e32 v125, v122, v126
	v_max_f32_e32 v122, v120, v129
	v_min_f32_e32 v126, v120, v129
	v_max_f32_e32 v120, v124, v123
	v_min_f32_e32 v129, v124, v123
	v_max_f32_e32 v124, v122, v127
	v_min_f32_e32 v123, v122, v127
	v_max_f32_e32 v122, v126, v128
	v_min_f32_e32 v127, v126, v128
	v_max_f32_e32 v126, v106, v118
	v_min_f32_e32 v128, v106, v118
	v_max_f32_e32 v106, v115, v123
	v_min_f32_e32 v118, v115, v123
	v_max_f32_e32 v115, v106, v128
	v_min_f32_e32 v123, v106, v128
	v_max_f32_e32 v106, v121, v129
	v_min_f32_e32 v128, v121, v129
	v_max_f32_e32 v121, v119, v127
	v_min_f32_e32 v129, v119, v127
	v_max_f32_e32 v119, v121, v128
	v_min_f32_e32 v127, v121, v128
	v_max_f32_e32 v121, v106, v115
	v_min_f32_e32 v128, v106, v115
	v_max_f32_e32 v106, v119, v123
	v_min_f32_e32 v115, v119, v123
	v_max_f32_e32 v119, v127, v118
	v_min_f32_e32 v123, v127, v118
	v_max_f32_e32 v127, v113, v120
	v_min_f32_e32 v118, v113, v120
	v_max_f32_e32 v113, v114, v122
	v_min_f32_e32 v120, v114, v122
	v_max_f32_e32 v114, v113, v118
	v_min_f32_e32 v122, v113, v118
	v_max_f32_e32 v113, v116, v124
	v_min_f32_e32 v118, v116, v124
	v_max_f32_e32 v116, v117, v125
	v_min_f32_e32 v124, v117, v125
	v_max_f32_e32 v117, v116, v118
	v_min_f32_e32 v125, v116, v118
	v_max_f32_e32 v116, v113, v114
	v_min_f32_e32 v118, v113, v114
	v_max_f32_e32 v113, v117, v122
	v_min_f32_e32 v114, v117, v122
	v_max_f32_e32 v117, v125, v120
	v_min_f32_e32 v122, v125, v120
	v_max_f32_e32 v125, v127, v121
	v_min_f32_e32 v120, v127, v121
	v_max_f32_e32 v127, v116, v128
	v_min_f32_e32 v121, v116, v128
	v_max_f32_e32 v116, v118, v106
	v_min_f32_e32 v128, v118, v106
	v_max_f32_e32 v118, v113, v115
	v_min_f32_e32 v106, v113, v115
	v_max_f32_e32 v113, v114, v119
	v_min_f32_e32 v115, v114, v119
	v_max_f32_e32 v114, v117, v123
	v_min_f32_e32 v119, v117, v123
	v_max_f32_e32 v117, v122, v129
	v_min_f32_e32 v123, v122, v129
	v_max_f32_e32 v122, v110, v124
	v_max_f32_e32 v129, v109, v123
	v_max_f32_e32 v110, v104, v117
	v_max_f32_e32 v124, v111, v119
	v_max_f32_e32 v109, v105, v114
	v_max_f32_e32 v123, v100, v115
	v_max_f32_e32 v104, v112, v113
	v_max_f32_e32 v117, v102, v106
	v_max_f32_e32 v111, v18, v118
	v_max_f32_e32 v119, v19, v128
	v_max_f32_e32 v105, v99, v116
	v_max_f32_e32 v114, v98, v121
	v_max_f32_e32 v100, v103, v127
	v_max_f32_e32 v115, v101, v120
	v_max_f32_e32 v112, v107, v125
	v_max_f32_e32 v113, v108, v126
	v_max_f32_e32 v102, v122, v111
	v_min_f32_e32 v106, v122, v111
	v_max_f32_e32 v18, v129, v119
	v_min_f32_e32 v118, v129, v119
	v_max_f32_e32 v19, v110, v105
	v_min_f32_e32 v128, v110, v105
	v_max_f32_e32 v99, v124, v114
	v_min_f32_e32 v116, v124, v114
	v_max_f32_e32 v98, v109, v100
	v_min_f32_e32 v121, v109, v100
	v_max_f32_e32 v103, v123, v115
	v_min_f32_e32 v127, v123, v115
	v_max_f32_e32 v101, v104, v112
	v_min_f32_e32 v120, v104, v112
	v_max_f32_e32 v107, v117, v113
	v_min_f32_e32 v125, v117, v113
	v_max_f32_e32 v108, v102, v98
	v_min_f32_e32 v126, v102, v98
	v_max_f32_e32 v122, v18, v103
	v_min_f32_e32 v111, v18, v103
	v_max_f32_e32 v129, v19, v101
	v_min_f32_e32 v119, v19, v101
	v_max_f32_e32 v110, v99, v107
	v_min_f32_e32 v105, v99, v107
	v_max_f32_e32 v124, v106, v121
	v_min_f32_e32 v114, v106, v121
	v_max_f32_e32 v109, v118, v127
	v_min_f32_e32 v100, v118, v127
	v_max_f32_e32 v123, v128, v120
	v_min_f32_e32 v115, v128, v120
	v_max_f32_e32 v104, v116, v125
	v_min_f32_e32 v112, v116, v125
	v_max_f32_e32 v117, v108, v129
	v_min_f32_e32 v113, v108, v129
	v_max_f32_e32 v102, v122, v110
	v_min_f32_e32 v98, v122, v110
	v_max_f32_e32 v18, v126, v119
	v_min_f32_e32 v103, v126, v119
	v_max_f32_e32 v19, v111, v105
	v_min_f32_e32 v101, v111, v105
	v_max_f32_e32 v99, v124, v123
	v_min_f32_e32 v107, v124, v123
	v_max_f32_e32 v106, v109, v104
	v_min_f32_e32 v121, v109, v104
	v_max_f32_e32 v118, v114, v115
	v_min_f32_e32 v127, v114, v115
	v_max_f32_e32 v128, v100, v112
	v_min_f32_e32 v120, v100, v112
	v_max_f32_e32 v116, v117, v102
	v_min_f32_e32 v125, v117, v102
	v_max_f32_e32 v108, v113, v98
	v_min_f32_e32 v129, v113, v98
	v_max_f32_e32 v122, v18, v19
	v_min_f32_e32 v110, v18, v19
	v_max_f32_e32 v126, v103, v101
	v_min_f32_e32 v119, v103, v101
	v_max_f32_e32 v111, v99, v106
	v_min_f32_e32 v105, v99, v106
	v_max_f32_e32 v124, v107, v121
	v_min_f32_e32 v123, v107, v121
	v_max_f32_e32 v109, v118, v128
	v_min_f32_e32 v104, v118, v128
	v_max_f32_e32 v114, v127, v120
	v_min_f32_e32 v115, v127, v120
	s_waitcnt lgkmcnt(8)
	v_and_b32_e32 v162, 0xffffff80, v162
	v_or3_b32 v162, v155, v162, 32
	v_and_b32_e32 v163, 0xffffff80, v163
	v_or3_b32 v163, v155, v163, 33
	v_and_b32_e32 v164, 0xffffff80, v164
	v_or3_b32 v164, v155, v164, 34
	v_and_b32_e32 v165, 0xffffff80, v165
	v_or3_b32 v165, v155, v165, 35
	v_and_b32_e32 v166, 0xffffff80, v166
	v_or3_b32 v166, v155, v166, 36
	v_and_b32_e32 v167, 0xffffff80, v167
	v_or3_b32 v167, v155, v167, 37
	v_and_b32_e32 v168, 0xffffff80, v168
	v_or3_b32 v168, v155, v168, 38
	v_and_b32_e32 v169, 0xffffff80, v169
	v_or3_b32 v169, v155, v169, 39
	v_and_b32_e32 v170, 0xffffff80, v170
	v_or3_b32 v170, v155, v170, 40
	v_and_b32_e32 v171, 0xffffff80, v171
	v_or3_b32 v171, v155, v171, 41
	v_and_b32_e32 v172, 0xffffff80, v172
	v_or3_b32 v172, v155, v172, 42
	v_and_b32_e32 v173, 0xffffff80, v173
	v_or3_b32 v173, v155, v173, 43
	v_and_b32_e32 v174, 0xffffff80, v174
	v_or3_b32 v174, v155, v174, 44
	v_and_b32_e32 v175, 0xffffff80, v175
	v_or3_b32 v175, v155, v175, 45
	v_and_b32_e32 v176, 0xffffff80, v176
	v_or3_b32 v176, v155, v176, 46
	v_and_b32_e32 v177, 0xffffff80, v177
	v_or3_b32 v177, v155, v177, 47
	v_max_f32_e32 v100, v162, v163
	v_min_f32_e32 v112, v162, v163
	v_max_f32_e32 v117, v164, v165
	v_min_f32_e32 v102, v164, v165
	v_max_f32_e32 v113, v100, v117
	v_min_f32_e32 v98, v100, v117
	v_max_f32_e32 v18, v112, v102
	v_min_f32_e32 v19, v112, v102
	v_max_f32_e32 v103, v18, v98
	v_min_f32_e32 v101, v18, v98
	v_max_f32_e32 v99, v166, v167
	v_min_f32_e32 v106, v166, v167
	v_max_f32_e32 v107, v168, v169
	v_min_f32_e32 v121, v168, v169
	v_max_f32_e32 v118, v99, v107
	v_min_f32_e32 v128, v99, v107
	v_max_f32_e32 v127, v106, v121
	v_min_f32_e32 v120, v106, v121
	v_max_f32_e32 v162, v127, v128
	v_min_f32_e32 v163, v127, v128
	v_max_f32_e32 v164, v113, v118
	v_min_f32_e32 v165, v113, v118
	v_max_f32_e32 v100, v101, v163
	v_min_f32_e32 v117, v101, v163
	v_max_f32_e32 v112, v100, v165
	v_min_f32_e32 v102, v100, v165
	v_max_f32_e32 v18, v103, v162
	v_min_f32_e32 v98, v103, v162
	v_max_f32_e32 v166, v19, v120
	v_min_f32_e32 v167, v19, v120
	v_max_f32_e32 v168, v166, v98
	v_min_f32_e32 v169, v166, v98
	v_max_f32_e32 v99, v18, v112
	v_min_f32_e32 v107, v18, v112
	v_max_f32_e32 v106, v168, v102
	v_min_f32_e32 v121, v168, v102
	v_max_f32_e32 v127, v169, v117
	v_min_f32_e32 v128, v169, v117
	v_max_f32_e32 v113, v170, v171
	v_min_f32_e32 v118, v170, v171
	v_max_f32_e32 v101, v172, v173
	v_min_f32_e32 v163, v172, v173
	v_max_f32_e32 v100, v113, v101
	v_min_f32_e32 v165, v113, v101
	v_max_f32_e32 v103, v118, v163
	v_min_f32_e32 v162, v118, v163
	v_max_f32_e32 v19, v103, v165
	v_min_f32_e32 v120, v103, v165
	v_max_f32_e32 v166, v174, v175
	v_min_f32_e32 v98, v174, v175
	v_max_f32_e32 v18, v176, v177
	v_min_f32_e32 v112, v176, v177
	v_max_f32_e32 v168, v166, v18
	v_min_f32_e32 v102, v166, v18
	v_max_f32_e32 v169, v98, v112
	v_min_f32_e32 v117, v98, v112
	v_max_f32_e32 v170, v169, v102
	v_min_f32_e32 v171, v169, v102
	v_max_f32_e32 v172, v100, v168
	v_min_f32_e32 v173, v100, v168
	v_max_f32_e32 v113, v120, v171
	v_min_f32_e32 v101, v120, v171
	v_max_f32_e32 v118, v113, v173
	v_min_f32_e32 v163, v113, v173
	v_max_f32_e32 v103, v19, v170
	v_min_f32_e32 v165, v19, v170
	v_max_f32_e32 v174, v162, v117
	v_min_f32_e32 v175, v162, v117
	v_max_f32_e32 v176, v174, v165
	v_min_f32_e32 v177, v174, v165
	v_max_f32_e32 v166, v103, v118
	v_min_f32_e32 v18, v103, v118
	v_max_f32_e32 v98, v176, v163
	v_min_f32_e32 v112, v176, v163
	v_max_f32_e32 v169, v177, v101
	v_min_f32_e32 v102, v177, v101
	v_max_f32_e32 v100, v164, v172
	v_min_f32_e32 v168, v164, v172
	v_max_f32_e32 v120, v121, v112
	v_min_f32_e32 v171, v121, v112
	v_max_f32_e32 v113, v120, v168
	v_min_f32_e32 v173, v120, v168
	v_max_f32_e32 v19, v107, v18
	v_min_f32_e32 v170, v107, v18
	v_max_f32_e32 v162, v128, v102
	v_min_f32_e32 v117, v128, v102
	v_max_f32_e32 v174, v162, v170
	v_min_f32_e32 v165, v162, v170
	v_max_f32_e32 v103, v19, v113
	v_min_f32_e32 v118, v19, v113
	v_max_f32_e32 v176, v174, v173
	v_min_f32_e32 v163, v174, v173
	v_max_f32_e32 v177, v165, v171
	v_min_f32_e32 v101, v165, v171
	v_max_f32_e32 v164, v99, v166
	v_min_f32_e32 v172, v99, v166
	v_max_f32_e32 v121, v127, v169
	v_min_f32_e32 v112, v127, v169
	v_max_f32_e32 v120, v121, v172
	v_min_f32_e32 v168, v121, v172
	v_max_f32_e32 v107, v106, v98
	v_min_f32_e32 v18, v106, v98
	v_max_f32_e32 v128, v167, v175
	v_min_f32_e32 v102, v167, v175
	v_max_f32_e32 v162, v128, v18
	v_min_f32_e32 v170, v128, v18
	v_max_f32_e32 v19, v107, v120
	v_min_f32_e32 v113, v107, v120
	v_max_f32_e32 v174, v162, v168
	v_min_f32_e32 v173, v162, v168
	v_max_f32_e32 v165, v170, v112
	v_min_f32_e32 v171, v170, v112
	v_max_f32_e32 v99, v164, v103
	v_min_f32_e32 v166, v164, v103
	v_max_f32_e32 v127, v19, v118
	v_min_f32_e32 v169, v19, v118
	v_max_f32_e32 v121, v113, v176
	v_min_f32_e32 v172, v113, v176
	v_max_f32_e32 v106, v174, v163
	v_min_f32_e32 v98, v174, v163
	v_max_f32_e32 v167, v173, v177
	v_min_f32_e32 v175, v173, v177
	v_max_f32_e32 v128, v165, v101
	v_min_f32_e32 v18, v165, v101
	v_max_f32_e32 v107, v171, v117
	v_min_f32_e32 v120, v171, v117
	s_waitcnt lgkmcnt(0)
	v_and_b32_e32 v178, 0xffffff80, v178
	v_or3_b32 v178, v155, v178, 48
	v_and_b32_e32 v179, 0xffffff80, v179
	v_or3_b32 v179, v155, v179, 49
	v_and_b32_e32 v180, 0xffffff80, v180
	v_or3_b32 v180, v155, v180, 50
	v_and_b32_e32 v181, 0xffffff80, v181
	v_or3_b32 v181, v155, v181, 51
	v_and_b32_e32 v182, 0xffffff80, v182
	v_or3_b32 v182, v155, v182, 52
	v_and_b32_e32 v183, 0xffffff80, v183
	v_or3_b32 v183, v155, v183, 53
	v_and_b32_e32 v184, 0xffffff80, v184
	v_or3_b32 v184, v155, v184, 54
	v_and_b32_e32 v185, 0xffffff80, v185
	v_or3_b32 v185, v155, v185, 55
	v_and_b32_e32 v186, 0xffffff80, v186
	v_or3_b32 v186, v155, v186, 56
	v_and_b32_e32 v187, 0xffffff80, v187
	v_or3_b32 v187, v155, v187, 57
	v_and_b32_e32 v188, 0xffffff80, v188
	v_or3_b32 v188, v155, v188, 58
	v_and_b32_e32 v189, 0xffffff80, v189
	v_or3_b32 v189, v155, v189, 59
	v_and_b32_e32 v190, 0xffffff80, v190
	v_or3_b32 v190, v155, v190, 60
	v_and_b32_e32 v191, 0xffffff80, v191
	v_or3_b32 v191, v155, v191, 61
	v_and_b32_e32 v192, 0xffffff80, v192
	v_or3_b32 v192, v155, v192, 62
	v_and_b32_e32 v193, 0xffffff80, v193
	v_or3_b32 v193, v155, v193, 63
	v_max_f32_e32 v162, v178, v179
	v_min_f32_e32 v168, v178, v179
	v_max_f32_e32 v170, v180, v181
	v_min_f32_e32 v112, v180, v181
	v_max_f32_e32 v164, v162, v170
	v_min_f32_e32 v103, v162, v170
	v_max_f32_e32 v19, v168, v112
	v_min_f32_e32 v118, v168, v112
	v_max_f32_e32 v113, v19, v103
	v_min_f32_e32 v176, v19, v103
	v_max_f32_e32 v174, v182, v183
	v_min_f32_e32 v163, v182, v183
	v_max_f32_e32 v173, v184, v185
	v_min_f32_e32 v177, v184, v185
	v_max_f32_e32 v165, v174, v173
	v_min_f32_e32 v101, v174, v173
	v_max_f32_e32 v171, v163, v177
	v_min_f32_e32 v117, v163, v177
	v_max_f32_e32 v178, v171, v101
	v_min_f32_e32 v179, v171, v101
	v_max_f32_e32 v180, v164, v165
	v_min_f32_e32 v181, v164, v165
	v_max_f32_e32 v162, v176, v179
	v_min_f32_e32 v170, v176, v179
	v_max_f32_e32 v168, v162, v181
	v_min_f32_e32 v112, v162, v181
	v_max_f32_e32 v19, v113, v178
	v_min_f32_e32 v103, v113, v178
	v_max_f32_e32 v182, v118, v117
	v_min_f32_e32 v183, v118, v117
	v_max_f32_e32 v184, v182, v103
	v_min_f32_e32 v185, v182, v103
	v_max_f32_e32 v174, v19, v168
	v_min_f32_e32 v173, v19, v168
	v_max_f32_e32 v163, v184, v112
	v_min_f32_e32 v177, v184, v112
	v_max_f32_e32 v171, v185, v170
	v_min_f32_e32 v101, v185, v170
	v_max_f32_e32 v164, v186, v187
	v_min_f32_e32 v165, v186, v187
	v_max_f32_e32 v176, v188, v189
	v_min_f32_e32 v179, v188, v189
	v_max_f32_e32 v162, v164, v176
	v_min_f32_e32 v181, v164, v176
	v_max_f32_e32 v113, v165, v179
	v_min_f32_e32 v178, v165, v179
	v_max_f32_e32 v118, v113, v181
	v_min_f32_e32 v117, v113, v181
	v_max_f32_e32 v182, v190, v191
	v_min_f32_e32 v103, v190, v191
	v_max_f32_e32 v19, v192, v193
	v_min_f32_e32 v168, v192, v193
	v_max_f32_e32 v184, v182, v19
	v_min_f32_e32 v112, v182, v19
	v_max_f32_e32 v185, v103, v168
	v_min_f32_e32 v170, v103, v168
	v_max_f32_e32 v186, v185, v112
	v_min_f32_e32 v187, v185, v112
	v_max_f32_e32 v188, v162, v184
	v_min_f32_e32 v189, v162, v184
	v_max_f32_e32 v164, v117, v187
	v_min_f32_e32 v176, v117, v187
	v_max_f32_e32 v165, v164, v189
	v_min_f32_e32 v179, v164, v189
	v_max_f32_e32 v113, v118, v186
	v_min_f32_e32 v181, v118, v186
	v_max_f32_e32 v190, v178, v170
	v_min_f32_e32 v191, v178, v170
	v_max_f32_e32 v192, v190, v181
	v_min_f32_e32 v193, v190, v181
	v_max_f32_e32 v182, v113, v165
	v_min_f32_e32 v19, v113, v165
	v_max_f32_e32 v103, v192, v179
	v_min_f32_e32 v168, v192, v179
	v_max_f32_e32 v185, v193, v176
	v_min_f32_e32 v112, v193, v176
	v_max_f32_e32 v162, v180, v188
	v_min_f32_e32 v184, v180, v188
	v_max_f32_e32 v117, v177, v168
	v_min_f32_e32 v187, v177, v168
	v_max_f32_e32 v164, v117, v184
	v_min_f32_e32 v189, v117, v184
	v_max_f32_e32 v118, v173, v19
	v_min_f32_e32 v186, v173, v19
	v_max_f32_e32 v178, v101, v112
	v_min_f32_e32 v170, v101, v112
	v_max_f32_e32 v190, v178, v186
	v_min_f32_e32 v181, v178, v186
	v_max_f32_e32 v113, v118, v164
	v_min_f32_e32 v165, v118, v164
	v_max_f32_e32 v192, v190, v189
	v_min_f32_e32 v179, v190, v189
	v_max_f32_e32 v193, v181, v187
	v_min_f32_e32 v176, v181, v187
	v_max_f32_e32 v180, v174, v182
	v_min_f32_e32 v188, v174, v182
	v_max_f32_e32 v177, v171, v185
	v_min_f32_e32 v168, v171, v185
	v_max_f32_e32 v117, v177, v188
	v_min_f32_e32 v184, v177, v188
	v_max_f32_e32 v173, v163, v103
	v_min_f32_e32 v19, v163, v103
	v_max_f32_e32 v101, v183, v191
	v_min_f32_e32 v112, v183, v191
	v_max_f32_e32 v178, v101, v19
	v_min_f32_e32 v186, v101, v19
	v_max_f32_e32 v118, v173, v117
	v_min_f32_e32 v164, v173, v117
	v_max_f32_e32 v190, v178, v184
	v_min_f32_e32 v189, v178, v184
	v_max_f32_e32 v181, v186, v168
	v_min_f32_e32 v187, v186, v168
	v_max_f32_e32 v174, v180, v113
	v_min_f32_e32 v182, v180, v113
	v_max_f32_e32 v171, v118, v165
	v_min_f32_e32 v185, v118, v165
	v_max_f32_e32 v177, v164, v192
	v_min_f32_e32 v188, v164, v192
	v_max_f32_e32 v163, v190, v179
	v_min_f32_e32 v103, v190, v179
	v_max_f32_e32 v183, v189, v193
	v_min_f32_e32 v191, v189, v193
	v_max_f32_e32 v101, v181, v176
	v_min_f32_e32 v19, v181, v176
	v_max_f32_e32 v173, v187, v170
	v_min_f32_e32 v117, v187, v170
	v_max_f32_e32 v178, v100, v112
	v_max_f32_e32 v184, v99, v117
	v_max_f32_e32 v186, v166, v173
	v_max_f32_e32 v168, v127, v19
	v_max_f32_e32 v180, v169, v101
	v_max_f32_e32 v113, v121, v191
	v_max_f32_e32 v118, v172, v183
	v_max_f32_e32 v165, v106, v103
	v_max_f32_e32 v164, v98, v163
	v_max_f32_e32 v192, v167, v188
	v_max_f32_e32 v190, v175, v177
	v_max_f32_e32 v179, v128, v185
	v_max_f32_e32 v189, v18, v171
	v_max_f32_e32 v193, v107, v182
	v_max_f32_e32 v181, v120, v174
	v_max_f32_e32 v176, v102, v162
	v_max_f32_e32 v187, v178, v164
	v_min_f32_e32 v170, v178, v164
	v_max_f32_e32 v100, v184, v192
	v_min_f32_e32 v112, v184, v192
	v_max_f32_e32 v99, v186, v190
	v_min_f32_e32 v117, v186, v190
	v_max_f32_e32 v166, v168, v179
	v_min_f32_e32 v173, v168, v179
	v_max_f32_e32 v127, v180, v189
	v_min_f32_e32 v19, v180, v189
	v_max_f32_e32 v169, v113, v193
	v_min_f32_e32 v101, v113, v193
	v_max_f32_e32 v121, v118, v181
	v_min_f32_e32 v191, v118, v181
	v_max_f32_e32 v172, v165, v176
	v_min_f32_e32 v183, v165, v176
	v_max_f32_e32 v106, v187, v127
	v_min_f32_e32 v103, v187, v127
	v_max_f32_e32 v98, v100, v169
	v_min_f32_e32 v163, v100, v169
	v_max_f32_e32 v167, v99, v121
	v_min_f32_e32 v188, v99, v121
	v_max_f32_e32 v175, v166, v172
	v_min_f32_e32 v177, v166, v172
	v_max_f32_e32 v128, v170, v19
	v_min_f32_e32 v185, v170, v19
	v_max_f32_e32 v18, v112, v101
	v_min_f32_e32 v171, v112, v101
	v_max_f32_e32 v107, v117, v191
	v_min_f32_e32 v182, v117, v191
	v_max_f32_e32 v120, v173, v183
	v_min_f32_e32 v174, v173, v183
	v_max_f32_e32 v102, v106, v167
	v_min_f32_e32 v162, v106, v167
	v_max_f32_e32 v178, v98, v175
	v_min_f32_e32 v164, v98, v175
	v_max_f32_e32 v184, v103, v188
	v_min_f32_e32 v192, v103, v188
	v_max_f32_e32 v186, v163, v177
	v_min_f32_e32 v190, v163, v177
	v_max_f32_e32 v168, v128, v107
	v_min_f32_e32 v179, v128, v107
	v_max_f32_e32 v180, v18, v120
	v_min_f32_e32 v189, v18, v120
	v_max_f32_e32 v113, v185, v182
	v_min_f32_e32 v193, v185, v182
	v_max_f32_e32 v118, v171, v174
	v_min_f32_e32 v181, v171, v174
	v_max_f32_e32 v165, v102, v178
	v_min_f32_e32 v176, v102, v178
	v_max_f32_e32 v187, v162, v164
	v_min_f32_e32 v127, v162, v164
	v_max_f32_e32 v100, v184, v186
	v_min_f32_e32 v169, v184, v186
	v_max_f32_e32 v99, v192, v190
	v_min_f32_e32 v121, v192, v190
	v_max_f32_e32 v166, v168, v180
	v_min_f32_e32 v172, v168, v180
	v_max_f32_e32 v170, v179, v189
	v_min_f32_e32 v19, v179, v189
	v_max_f32_e32 v112, v113, v118
	v_min_f32_e32 v101, v113, v118
	v_max_f32_e32 v117, v193, v181
	v_min_f32_e32 v191, v193, v181
	v_max_f32_e32 v173, v116, v191
	v_max_f32_e32 v183, v125, v117
	v_max_f32_e32 v106, v108, v101
	v_max_f32_e32 v167, v129, v112
	v_max_f32_e32 v98, v122, v19
	v_max_f32_e32 v175, v110, v170
	v_max_f32_e32 v103, v126, v172
	v_max_f32_e32 v188, v119, v166
	v_max_f32_e32 v163, v111, v121
	v_max_f32_e32 v177, v105, v99
	v_max_f32_e32 v128, v124, v169
	v_max_f32_e32 v107, v123, v100
	v_max_f32_e32 v18, v109, v127
	v_max_f32_e32 v120, v104, v187
	v_max_f32_e32 v185, v114, v176
	v_max_f32_e32 v182, v115, v165
	v_max_f32_e32 v171, v173, v163
	v_min_f32_e32 v174, v173, v163
	v_max_f32_e32 v102, v183, v177
	v_min_f32_e32 v178, v183, v177
	v_max_f32_e32 v162, v106, v128
	v_min_f32_e32 v164, v106, v128
	v_max_f32_e32 v184, v167, v107
	v_min_f32_e32 v186, v167, v107
	v_max_f32_e32 v192, v98, v18
	v_min_f32_e32 v190, v98, v18
	v_max_f32_e32 v168, v175, v120
	v_min_f32_e32 v180, v175, v120
	v_max_f32_e32 v179, v103, v185
	v_min_f32_e32 v189, v103, v185
	v_max_f32_e32 v113, v188, v182
	v_min_f32_e32 v118, v188, v182
	v_max_f32_e32 v193, v171, v192
	v_min_f32_e32 v181, v171, v192
	v_max_f32_e32 v116, v102, v168
	v_min_f32_e32 v191, v102, v168
	v_max_f32_e32 v125, v162, v179
	v_min_f32_e32 v117, v162, v179
	v_max_f32_e32 v108, v184, v113
	v_min_f32_e32 v101, v184, v113
	v_max_f32_e32 v129, v174, v190
	v_min_f32_e32 v112, v174, v190
	v_max_f32_e32 v122, v178, v180
	v_min_f32_e32 v19, v178, v180
	v_max_f32_e32 v110, v164, v189
	v_min_f32_e32 v170, v164, v189
	v_max_f32_e32 v126, v186, v118
	v_min_f32_e32 v172, v186, v118
	v_max_f32_e32 v119, v193, v125
	v_min_f32_e32 v166, v193, v125
	v_max_f32_e32 v111, v116, v108
	v_min_f32_e32 v121, v116, v108
	v_max_f32_e32 v105, v181, v117
	v_min_f32_e32 v99, v181, v117
	v_max_f32_e32 v124, v191, v101
	v_min_f32_e32 v169, v191, v101
	v_max_f32_e32 v123, v129, v110
	v_min_f32_e32 v100, v129, v110
	v_max_f32_e32 v109, v122, v126
	v_min_f32_e32 v127, v122, v126
	v_max_f32_e32 v104, v112, v170
	v_min_f32_e32 v187, v112, v170
	v_max_f32_e32 v114, v19, v172
	v_min_f32_e32 v176, v19, v172
	v_max_f32_e32 v2, v119, v111
	v_min_f32_e32 v3, v119, v111
	v_max_f32_e32 v4, v166, v121
	v_min_f32_e32 v5, v166, v121
	v_max_f32_e32 v6, v105, v124
	v_min_f32_e32 v7, v105, v124
	v_max_f32_e32 v8, v99, v169
	v_min_f32_e32 v9, v99, v169
	v_max_f32_e32 v10, v123, v109
	v_min_f32_e32 v11, v123, v109
	v_max_f32_e32 v12, v100, v127
	v_min_f32_e32 v13, v100, v127
	v_max_f32_e32 v14, v104, v114
	v_min_f32_e32 v15, v104, v114
	v_max_f32_e32 v16, v187, v176
	v_min_f32_e32 v17, v187, v176
	s_and_saveexec_b64 s[4:5], s[40:41]
	s_cbranch_execz .LBB0_46
	ds_write_b128 v159, v[2:5]
	ds_write_b128 v159, v[6:9] offset:16
	ds_write_b128 v159, v[10:13] offset:32
	ds_write_b128 v159, v[14:17] offset:48
.LBB0_46:
	s_or_b64 exec, exec, s[4:5]
	s_waitcnt lgkmcnt(0)
	s_barrier
	s_and_saveexec_b64 s[4:5], s[42:43]
	s_cbranch_execz .LBB0_33
	ds_read_b128 v[22:25], v160
	ds_read_b128 v[26:29], v160 offset:16
	ds_read_b128 v[30:33], v160 offset:32
	ds_read_b128 v[18:21], v160 offset:48
	v_readlane_b32 s6, v251, 0
	v_readlane_b32 s7, v251, 1
	v_lshl_or_b32 v0, s14, 11, v130
	s_waitcnt lgkmcnt(0)
	v_max_f32_e32 v2, v2, v21
	v_max_f32_e32 v3, v3, v20
	v_max_f32_e32 v4, v4, v19
	v_max_f32_e32 v5, v5, v18
	v_max_f32_e32 v6, v6, v33
	v_max_f32_e32 v7, v7, v32
	v_max_f32_e32 v8, v8, v31
	v_max_f32_e32 v9, v9, v30
	v_max_f32_e32 v10, v10, v29
	v_max_f32_e32 v11, v11, v28
	v_max_f32_e32 v12, v12, v27
	v_max_f32_e32 v13, v13, v26
	v_max_f32_e32 v14, v14, v25
	v_max_f32_e32 v15, v15, v24
	v_max_f32_e32 v16, v16, v23
	v_max_f32_e32 v17, v17, v22
	v_max_f32_e32 v18, v2, v10
	v_min_f32_e32 v26, v2, v10
	v_max_f32_e32 v19, v3, v11
	v_min_f32_e32 v27, v3, v11
	v_max_f32_e32 v20, v4, v12
	v_min_f32_e32 v28, v4, v12
	v_max_f32_e32 v21, v5, v13
	v_min_f32_e32 v29, v5, v13
	v_max_f32_e32 v22, v6, v14
	v_min_f32_e32 v30, v6, v14
	v_max_f32_e32 v23, v7, v15
	v_min_f32_e32 v31, v7, v15
	v_max_f32_e32 v24, v8, v16
	v_min_f32_e32 v32, v8, v16
	v_max_f32_e32 v25, v9, v17
	v_min_f32_e32 v33, v9, v17
	v_max_f32_e32 v2, v18, v22
	v_min_f32_e32 v6, v18, v22
	v_max_f32_e32 v3, v19, v23
	v_min_f32_e32 v7, v19, v23
	v_max_f32_e32 v4, v20, v24
	v_min_f32_e32 v8, v20, v24
	v_max_f32_e32 v5, v21, v25
	v_min_f32_e32 v9, v21, v25
	v_max_f32_e32 v10, v26, v30
	v_min_f32_e32 v14, v26, v30
	v_max_f32_e32 v11, v27, v31
	v_min_f32_e32 v15, v27, v31
	v_max_f32_e32 v12, v28, v32
	v_min_f32_e32 v16, v28, v32
	v_max_f32_e32 v13, v29, v33
	v_min_f32_e32 v17, v29, v33
	v_max_f32_e32 v18, v2, v4
	v_min_f32_e32 v20, v2, v4
	v_max_f32_e32 v19, v3, v5
	v_min_f32_e32 v21, v3, v5
	v_max_f32_e32 v22, v6, v8
	v_min_f32_e32 v24, v6, v8
	v_max_f32_e32 v23, v7, v9
	v_min_f32_e32 v25, v7, v9
	v_max_f32_e32 v26, v10, v12
	v_min_f32_e32 v28, v10, v12
	v_max_f32_e32 v27, v11, v13
	v_min_f32_e32 v29, v11, v13
	v_max_f32_e32 v30, v14, v16
	v_min_f32_e32 v32, v14, v16
	v_max_f32_e32 v31, v15, v17
	v_min_f32_e32 v33, v15, v17
	v_max_f32_e32 v2, v18, v19
	v_min_f32_e32 v3, v18, v19
	v_max_f32_e32 v4, v20, v21
	v_min_f32_e32 v5, v20, v21
	v_max_f32_e32 v6, v22, v23
	v_min_f32_e32 v7, v22, v23
	v_max_f32_e32 v8, v24, v25
	v_min_f32_e32 v9, v24, v25
	v_max_f32_e32 v10, v26, v27
	v_min_f32_e32 v11, v26, v27
	v_max_f32_e32 v12, v28, v29
	v_min_f32_e32 v13, v28, v29
	v_max_f32_e32 v14, v30, v31
	v_min_f32_e32 v15, v30, v31
	v_max_f32_e32 v16, v32, v33
	v_min_f32_e32 v17, v32, v33
	v_lshl_add_u64 v[18:19], v[0:1], 2, s[6:7]
	global_store_dwordx4 v[18:19], v[2:5], off
	global_store_dwordx4 v[18:19], v[6:9], off offset:16
	global_store_dwordx4 v[18:19], v[10:13], off offset:32
	global_store_dwordx4 v[18:19], v[14:17], off offset:48
	s_branch .LBB0_33
